# MLA/NA attention loops: blanket vmcnt(0) before the register-staged K/V LDS writes removed (per-write counted waits remain), on top of S-loop rotation + tree trim
# baseline (speedup 1.0000x reference)
.LBB0_2226:
	s_add_i32 s2, s58, -1
	s_add_i32 s13, s58, -2
	ds_read_b128 v[66:69], v171 offset:49152
	ds_read_b128 v[70:73], v171 offset:57344
	ds_read_b128 v[192:195], v172 offset:49152
	ds_read_b128 v[196:199], v172 offset:57344
	v_exp_f32_e32 v140, v140
	v_exp_f32_e32 v141, v141
	s_waitcnt lgkmcnt(3)
	v_mfma_f32_32x32x16_bf16 v[82:97], v[66:69], v[126:129], 0
	v_exp_f32_e32 v139, v139
	v_exp_f32_e32 v208, v135
	v_exp_f32_e32 v209, v132
	v_exp_f32_e32 v144, v144
	v_exp_f32_e32 v145, v145
	s_waitcnt lgkmcnt(2)
	v_mfma_f32_32x32x16_bf16 v[66:81], v[70:73], v[126:129], 0
	s_waitcnt lgkmcnt(0)
	v_mfma_f32_32x32x16_bf16 v[66:81], v[196:199], v[122:125], v[66:81]
	v_mfma_f32_32x32x16_bf16 v[82:97], v[192:195], v[122:125], v[82:97]
	ds_read_b128 v[192:195], v173 offset:49152
	ds_read_b128 v[196:199], v173 offset:57344
	s_waitcnt lgkmcnt(0)
	v_mfma_f32_32x32x16_bf16 v[66:81], v[196:199], v[118:121], v[66:81]
	v_mfma_f32_32x32x16_bf16 v[82:97], v[192:195], v[118:121], v[82:97]
	ds_read_b128 v[192:195], v174 offset:49152
	ds_read_b128 v[196:199], v174 offset:57344
	s_waitcnt lgkmcnt(0)
	v_mfma_f32_32x32x16_bf16 v[66:81], v[196:199], v[114:117], v[66:81]
	v_mfma_f32_32x32x16_bf16 v[82:97], v[192:195], v[114:117], v[82:97]
	ds_read_b128 v[192:195], v175 offset:49152
	ds_read_b128 v[196:199], v175 offset:57344
	s_waitcnt lgkmcnt(0)
	v_mfma_f32_32x32x16_bf16 v[66:81], v[196:199], v[110:113], v[66:81]
	v_mfma_f32_32x32x16_bf16 v[82:97], v[192:195], v[110:113], v[82:97]
	ds_read_b128 v[192:195], v176 offset:49152
	ds_read_b128 v[196:199], v176 offset:57344
	s_waitcnt lgkmcnt(0)
	v_mfma_f32_32x32x16_bf16 v[66:81], v[196:199], v[106:109], v[66:81]
	v_mfma_f32_32x32x16_bf16 v[82:97], v[192:195], v[106:109], v[82:97]
	ds_read_b128 v[192:195], v177 offset:49152
	ds_read_b128 v[196:199], v177 offset:57344
	s_waitcnt lgkmcnt(0)
	v_mfma_f32_32x32x16_bf16 v[66:81], v[196:199], v[102:105], v[66:81]
	v_mfma_f32_32x32x16_bf16 v[82:97], v[192:195], v[102:105], v[82:97]
	ds_read_b128 v[192:195], v179 offset:49152
	ds_read_b128 v[196:199], v179 offset:57344
	s_waitcnt lgkmcnt(0)
	v_mfma_f32_32x32x16_bf16 v[66:81], v[196:199], v[98:101], v[66:81]
	v_mfma_f32_32x32x16_bf16 v[82:97], v[192:195], v[98:101], v[82:97]
	v_add_u32_e32 v192, v164, v157
	ds_read_b128 v[194:197], v192
	ds_read_b128 v[218:221], v192 offset:4096
	ds_read_b128 v[222:225], v189
	v_add_u32_e32 v193, v164, v158
	s_waitcnt lgkmcnt(0)
	v_mfma_f32_32x32x16_bf16 v[66:81], v[218:221], v[222:225], v[66:81]
	v_mfma_f32_32x32x16_bf16 v[82:97], v[194:197], v[222:225], v[82:97]
	ds_read_b128 v[194:197], v193
	ds_read_b128 v[218:221], v193 offset:4096
	ds_read_b128 v[222:225], v189 offset:1024
	s_waitcnt lgkmcnt(0)
	v_mfma_f32_32x32x16_bf16 v[66:81], v[218:221], v[222:225], v[66:81]
	v_mfma_f32_32x32x16_bf16 v[82:97], v[194:197], v[222:225], v[82:97]
	v_add_u32_e32 v194, v164, v159
	ds_read_b128 v[196:199], v194
	ds_read_b128 v[218:221], v194 offset:4096
	ds_read_b128 v[222:225], v189 offset:2048
	v_add_u32_e32 v195, v164, v160
	s_waitcnt lgkmcnt(0)
	v_mfma_f32_32x32x16_bf16 v[66:81], v[218:221], v[222:225], v[66:81]
	v_mfma_f32_32x32x16_bf16 v[82:97], v[196:199], v[222:225], v[82:97]
	ds_read_b128 v[196:199], v195
	ds_read_b128 v[218:221], v195 offset:4096
	ds_read_b128 v[222:225], v189 offset:3072
	s_waitcnt lgkmcnt(0)
	v_mfma_f32_32x32x16_bf16 v[66:81], v[218:221], v[222:225], v[66:81]
	v_exp_f32_e32 v219, v130
	v_add_f32_e32 v130, 0, v215
	v_add_f32_e32 v130, v217, v130
	v_add_f32_e32 v130, v213, v130
	v_add_f32_e32 v130, v216, v130
	v_add_f32_e32 v130, v212, v130
	v_add_f32_e32 v130, v214, v130
	v_add_f32_e32 v130, v210, v130
	v_add_f32_e32 v130, v211, v130
	v_add_f32_e32 v130, v205, v130
	v_add_f32_e32 v130, v207, v130
	v_add_f32_e32 v130, v204, v130
	v_add_f32_e32 v130, v206, v130
	v_add_f32_e32 v130, v201, v130
	v_add_f32_e32 v130, v203, v130
	v_mfma_f32_32x32x16_bf16 v[82:97], v[196:199], v[222:225], v[82:97]
	v_exp_f32_e32 v198, v138
	v_add_f32_e32 v130, v200, v130
	v_add_f32_e32 v130, v202, v130
	v_exp_f32_e32 v199, v134
	v_add_f32_e32 v130, v140, v130
	v_add_f32_e32 v130, v141, v130
	v_add_f32_e32 v130, v198, v130
	v_exp_f32_e32 v218, v133
	v_add_f32_e32 v130, v139, v130
	v_add_f32_e32 v130, v199, v130
	v_exp_f32_e32 v220, v131
	v_add_f32_e32 v130, v208, v130
	v_add_f32_e32 v130, v209, v130
	v_add_f32_e32 v130, v218, v130
	v_exp_f32_e32 v221, v142
	v_add_f32_e32 v130, v219, v130
	v_exp_f32_e32 v222, v143
	v_add_f32_e32 v130, v220, v130
	v_exp_f32_e32 v223, v136
	v_add_f32_e32 v130, v144, v130
	v_exp_f32_e32 v224, v137
	v_add_f32_e32 v130, v145, v130
	v_add_f32_e32 v130, v221, v130
	v_add_f32_e32 v130, v222, v130
	v_add_f32_e32 v130, v223, v130
	v_add_f32_e32 v196, v224, v130
	v_mov_b32_e32 v197, v196
	v_cvt_pk_bf16_f32 v130, v215, v217
	v_cvt_pk_bf16_f32 v131, v213, v216
	v_cvt_pk_bf16_f32 v132, v212, v214
	s_nop 1
	v_permlane32_swap_b32_e32 v196, v197
	v_cvt_pk_bf16_f32 v133, v210, v211
	v_permlane32_swap_b32_e32 v130, v132
	v_cvt_pk_bf16_f32 v134, v205, v207
	v_cvt_pk_bf16_f32 v135, v204, v206
	v_cvt_pk_bf16_f32 v136, v201, v203
	v_cvt_pk_bf16_f32 v137, v200, v202
	v_cvt_pk_bf16_f32 v138, v140, v141
	v_cvt_pk_bf16_f32 v139, v198, v139
	v_cvt_pk_bf16_f32 v140, v199, v208
	v_cvt_pk_bf16_f32 v141, v209, v218
	v_cvt_pk_bf16_f32 v142, v219, v220
	v_cvt_pk_bf16_f32 v143, v144, v145
	v_cvt_pk_bf16_f32 v144, v221, v222
	v_cvt_pk_bf16_f32 v145, v223, v224
	v_permlane32_swap_b32_e32 v131, v133
	v_permlane32_swap_b32_e32 v134, v136
	v_permlane32_swap_b32_e32 v135, v137
	v_permlane32_swap_b32_e32 v138, v140
	v_permlane32_swap_b32_e32 v139, v141
	v_permlane32_swap_b32_e32 v142, v144
	v_permlane32_swap_b32_e32 v143, v145
	s_min_i32 s3, s2, s8
	s_cmp_lt_u32 s13, 3
	s_cselect_b32 s2, s2, s3
	s_lshl_b32 s2, s2, 6
	s_add_i32 s2, s2, s36
	s_ashr_i32 s3, s2, 31
	s_lshl_b64 s[10:11], s[2:3], 13
	v_lshl_add_u64 v[198:199], v[152:153], 0, s[10:11]
	s_bitset1_b32 s10, 18
	v_lshl_add_u64 v[208:209], v[154:155], 0, s[10:11]
	global_load_dwordx4 v[200:203], v[198:199], off offset:256
	global_load_dwordx4 v[204:207], v[198:199], off
	v_lshl_add_u64 v[198:199], v[152:153], 0, s[10:11]
	s_lshl_b64 s[2:3], s[2:3], 7
	global_load_dwordx4 v[208:211], v[208:209], off
	s_nop 0
	global_load_dwordx4 v[212:215], v[198:199], off
	v_lshl_add_u64 v[198:199], v[148:149], 0, s[2:3]
	global_load_dwordx4 v[216:219], v[198:199], off
	ds_read_b64_tr_b16 v[220:221], v163 offset:0
	ds_read_b64_tr_b16 v[222:223], v163 offset:0x800
	ds_read_b64_tr_b16 v[224:225], v163 offset:0x1000
	ds_read_b64_tr_b16 v[226:227], v163 offset:0x1800
	ds_read_b64_tr_b16 v[228:229], v163 offset:0x2000
	ds_read_b64_tr_b16 v[230:231], v163 offset:0x2800
	ds_read_b64_tr_b16 v[232:233], v163 offset:0x3000
	ds_read_b64_tr_b16 v[234:235], v163 offset:0x3800
	s_waitcnt lgkmcnt(0)
	s_nop 0
	v_mfma_f32_32x32x16_bf16 v[34:49], v[130:133], v[220:223], v[34:49]
	ds_read_b64_tr_b16 v[220:221], v163 offset:0x200
	ds_read_b64_tr_b16 v[222:223], v163 offset:0xa00
	v_mfma_f32_32x32x16_bf16 v[34:49], v[134:137], v[224:227], v[34:49]
	ds_read_b64_tr_b16 v[224:225], v163 offset:0x1200
	ds_read_b64_tr_b16 v[226:227], v163 offset:0x1a00
	v_mfma_f32_32x32x16_bf16 v[34:49], v[138:141], v[228:231], v[34:49]
	ds_read_b64_tr_b16 v[228:229], v163 offset:0x2200
	ds_read_b64_tr_b16 v[230:231], v163 offset:0x2a00
	ds_read_b64_tr_b16 v[236:237], v163 offset:0x3200
	ds_read_b64_tr_b16 v[238:239], v163 offset:0x3a00
	s_waitcnt lgkmcnt(0)
	v_mfma_f32_32x32x16_bf16 v[34:49], v[142:145], v[232:235], v[34:49]
	v_mfma_f32_32x32x16_bf16 v[18:33], v[130:133], v[220:223], v[18:33]
	ds_read_b64_tr_b16 v[220:221], v163 offset:0x400
	ds_read_b64_tr_b16 v[222:223], v163 offset:0xc00
	v_mfma_f32_32x32x16_bf16 v[18:33], v[134:137], v[224:227], v[18:33]
	ds_read_b64_tr_b16 v[224:225], v163 offset:0x1400
	ds_read_b64_tr_b16 v[226:227], v163 offset:0x1c00
	v_mfma_f32_32x32x16_bf16 v[18:33], v[138:141], v[228:231], v[18:33]
	ds_read_b64_tr_b16 v[228:229], v163 offset:0x2400
	ds_read_b64_tr_b16 v[230:231], v163 offset:0x2c00
	ds_read_b64_tr_b16 v[232:233], v163 offset:0x3400
	ds_read_b64_tr_b16 v[234:235], v163 offset:0x3c00
	s_waitcnt lgkmcnt(0)
	v_mfma_f32_32x32x16_bf16 v[18:33], v[142:145], v[236:239], v[18:33]
	v_mfma_f32_32x32x16_bf16 v[2:17], v[130:133], v[220:223], v[2:17]
	ds_read_b64_tr_b16 v[220:221], v163 offset:0x600
	ds_read_b64_tr_b16 v[222:223], v163 offset:0xe00
	v_mfma_f32_32x32x16_bf16 v[2:17], v[134:137], v[224:227], v[2:17]
	ds_read_b64_tr_b16 v[224:225], v163 offset:0x1600
	ds_read_b64_tr_b16 v[226:227], v163 offset:0x1e00
	v_mfma_f32_32x32x16_bf16 v[2:17], v[138:141], v[228:231], v[2:17]
	ds_read_b64_tr_b16 v[228:229], v163 offset:0x2600
	ds_read_b64_tr_b16 v[230:231], v163 offset:0x2e00
	ds_read_b64_tr_b16 v[236:237], v163 offset:0x3600
	ds_read_b64_tr_b16 v[238:239], v163 offset:0x3e00
	s_waitcnt lgkmcnt(0)
	v_mfma_f32_32x32x16_bf16 v[2:17], v[142:145], v[232:235], v[2:17]
	v_mfma_f32_32x32x16_bf16 v[50:65], v[130:133], v[220:223], v[50:65]
	v_max_f32_e32 v198, v83, v83
	v_max_f32_e32 v199, v82, v82
	v_max_f32_e32 v198, v199, v198
	v_max3_f32 v198, v198, v84, v85
	v_max3_f32 v198, v198, v86, v87
	v_max3_f32 v130, v198, v88, v89
	v_max3_f32 v130, v130, v90, v91
	v_max3_f32 v130, v130, v92, v93
	v_mfma_f32_32x32x16_bf16 v[50:65], v[134:137], v[224:227], v[50:65]
	v_max3_f32 v130, v130, v94, v95
	v_max3_f32 v130, v130, v96, v97
	v_max3_f32 v130, v130, v66, v67
	v_max3_f32 v130, v130, v68, v69
	v_max3_f32 v130, v130, v70, v71
	v_max3_f32 v130, v130, v72, v73
	v_max3_f32 v130, v130, v74, v75
	v_max3_f32 v130, v130, v76, v77
	v_mfma_f32_32x32x16_bf16 v[50:65], v[138:141], v[228:231], v[50:65]
	v_max3_f32 v130, v130, v78, v79
	v_max3_f32 v130, v130, v80, v81
	v_mov_b32_e32 v131, v130
	s_nop 1
	v_permlane32_swap_b32_e32 v130, v131
	v_max_f32_e32 v131, v131, v131
	v_max_f32_e32 v130, v130, v130
	v_max_f32_e32 v130, v130, v131
	v_max_f32_e32 v132, v191, v191
	v_sub_f32_e32 v131, v130, v191
	v_max_f32_e32 v130, v132, v130
	v_mfma_f32_32x32x16_bf16 v[50:65], v[142:145], v[236:239], v[50:65]
	v_sub_f32_e32 v132, v191, v130
	v_mul_f32_e32 v132, 0x3fb8aa3b, v132
	v_exp_f32_e32 v132, v132
	v_cmp_ge_f32_e32 vcc, s54, v131
	s_cmp_eq_u64 vcc, exec
	s_cselect_b64 s[2:3], -1, 0
	s_barrier
	v_cndmask_b32_e64 v199, v132, 1.0, s[2:3]
	v_cmp_gt_f32_e32 vcc, 1.0, v199
	s_waitcnt vmcnt(4)
	ds_write_b128 v166, v[200:203]
	s_waitcnt vmcnt(2)
	ds_write_b128 v167, v[208:211]
	ds_write_b128 v168, v[204:207] offset:32768
	s_waitcnt vmcnt(1)
	ds_write_b128 v169, v[212:215] offset:32768
	s_waitcnt vmcnt(0)
	ds_write_b128 v170, v[216:219]
	s_cbranch_vccz .LBB0_2230
	s_and_saveexec_b64 s[10:11], s[0:1]
	ds_write_b32 v188, v199 offset:128
	s_or_b64 exec, exec, s[10:11]
	s_waitcnt lgkmcnt(0)
	v_add_u32_e32 v131, s56, v156
	ds_read_b128 v[132:135], v131 offset:224
	ds_read_b128 v[136:139], v131 offset:192
	ds_read_b128 v[140:143], v131 offset:160
	ds_read_b128 v[200:203], v131 offset:128
	s_waitcnt lgkmcnt(3)
	v_pk_mul_f32 v[46:47], v[46:47], v[132:133]
	s_waitcnt lgkmcnt(2)
	v_pk_mul_f32 v[42:43], v[42:43], v[136:137]
	s_waitcnt lgkmcnt(1)
	v_pk_mul_f32 v[38:39], v[38:39], v[140:141]
	v_pk_mul_f32 v[48:49], v[48:49], v[134:135]
	v_pk_mul_f32 v[44:45], v[44:45], v[138:139]
	v_pk_mul_f32 v[40:41], v[40:41], v[142:143]
	s_waitcnt lgkmcnt(0)
	v_pk_mul_f32 v[36:37], v[36:37], v[202:203]
	v_pk_mul_f32 v[34:35], v[34:35], v[200:201]
	v_pk_mul_f32 v[30:31], v[30:31], v[132:133]
	v_pk_mul_f32 v[26:27], v[26:27], v[136:137]
	v_pk_mul_f32 v[22:23], v[22:23], v[140:141]
	v_pk_mul_f32 v[32:33], v[32:33], v[134:135]
	v_pk_mul_f32 v[28:29], v[28:29], v[138:139]
	v_pk_mul_f32 v[24:25], v[24:25], v[142:143]
	v_pk_mul_f32 v[20:21], v[20:21], v[202:203]
	v_pk_mul_f32 v[18:19], v[18:19], v[200:201]
	v_pk_mul_f32 v[14:15], v[14:15], v[132:133]
	v_pk_mul_f32 v[10:11], v[10:11], v[136:137]
	v_pk_mul_f32 v[6:7], v[6:7], v[140:141]
	v_pk_mul_f32 v[16:17], v[16:17], v[134:135]
	v_pk_mul_f32 v[12:13], v[12:13], v[138:139]
	v_pk_mul_f32 v[8:9], v[8:9], v[142:143]
	v_pk_mul_f32 v[4:5], v[4:5], v[202:203]
	v_pk_mul_f32 v[2:3], v[2:3], v[200:201]
	v_pk_mul_f32 v[62:63], v[62:63], v[132:133]
	v_pk_mul_f32 v[58:59], v[58:59], v[136:137]
	v_pk_mul_f32 v[54:55], v[54:55], v[140:141]
	v_pk_mul_f32 v[64:65], v[64:65], v[134:135]
	v_pk_mul_f32 v[60:61], v[60:61], v[138:139]
	v_pk_mul_f32 v[56:57], v[56:57], v[142:143]
	v_pk_mul_f32 v[52:53], v[52:53], v[202:203]
	v_pk_mul_f32 v[50:51], v[50:51], v[200:201]

.LBB0_2232:
	s_ashr_i32 s3, s2, 31
	s_lshl_b64 s[10:11], s[2:3], 13
	v_lshl_add_u64 v[204:205], v[152:153], 0, s[10:11]
	v_add_co_u32_e32 v214, vcc, 0x40000, v204
	s_lshl_b64 s[2:3], s[2:3], 7
	s_nop 0
	v_addc_co_u32_e32 v215, vcc, 0, v205, vcc
	global_load_dwordx4 v[200:203], v[204:205], off offset:256
	s_nop 0
	global_load_dwordx4 v[204:207], v[204:205], off
	s_nop 0
	global_load_dwordx4 v[210:213], v[214:215], off offset:256
	s_nop 0
	global_load_dwordx4 v[214:217], v[214:215], off
	v_lshl_add_u64 v[218:219], v[148:149], 0, s[2:3]
	global_load_dwordx4 v[218:221], v[218:219], off
	ds_read_b64_tr_b16 v[222:223], v165 offset:0
	ds_read_b64_tr_b16 v[224:225], v165 offset:0x800
	ds_read_b64_tr_b16 v[226:227], v165 offset:0x1000
	ds_read_b64_tr_b16 v[228:229], v165 offset:0x1800
	ds_read_b64_tr_b16 v[230:231], v165 offset:0x2000
	ds_read_b64_tr_b16 v[232:233], v165 offset:0x2800
	ds_read_b64_tr_b16 v[234:235], v165 offset:0x3000
	ds_read_b64_tr_b16 v[236:237], v165 offset:0x3800
	s_waitcnt lgkmcnt(0)
	s_nop 0
	v_mfma_f32_32x32x16_bf16 v[34:49], v[130:133], v[222:225], v[34:49]
	ds_read_b64_tr_b16 v[222:223], v165 offset:0x200
	ds_read_b64_tr_b16 v[224:225], v165 offset:0xa00
	v_mfma_f32_32x32x16_bf16 v[34:49], v[134:137], v[226:229], v[34:49]
	ds_read_b64_tr_b16 v[226:227], v165 offset:0x1200
	ds_read_b64_tr_b16 v[228:229], v165 offset:0x1a00
	v_mfma_f32_32x32x16_bf16 v[34:49], v[138:141], v[230:233], v[34:49]
	ds_read_b64_tr_b16 v[230:231], v165 offset:0x2200
	ds_read_b64_tr_b16 v[232:233], v165 offset:0x2a00
	ds_read_b64_tr_b16 v[238:239], v165 offset:0x3200
	ds_read_b64_tr_b16 v[240:241], v165 offset:0x3a00
	s_waitcnt lgkmcnt(0)
	v_mfma_f32_32x32x16_bf16 v[34:49], v[142:145], v[234:237], v[34:49]
	v_mfma_f32_32x32x16_bf16 v[18:33], v[130:133], v[222:225], v[18:33]
	ds_read_b64_tr_b16 v[222:223], v165 offset:0x400
	ds_read_b64_tr_b16 v[224:225], v165 offset:0xc00
	v_mfma_f32_32x32x16_bf16 v[18:33], v[134:137], v[226:229], v[18:33]
	ds_read_b64_tr_b16 v[226:227], v165 offset:0x1400
	ds_read_b64_tr_b16 v[228:229], v165 offset:0x1c00
	v_mfma_f32_32x32x16_bf16 v[18:33], v[138:141], v[230:233], v[18:33]
	ds_read_b64_tr_b16 v[230:231], v165 offset:0x2400
	ds_read_b64_tr_b16 v[232:233], v165 offset:0x2c00
	ds_read_b64_tr_b16 v[234:235], v165 offset:0x3400
	ds_read_b64_tr_b16 v[236:237], v165 offset:0x3c00
	s_waitcnt lgkmcnt(0)
	v_mfma_f32_32x32x16_bf16 v[18:33], v[142:145], v[238:241], v[18:33]
	v_mfma_f32_32x32x16_bf16 v[2:17], v[130:133], v[222:225], v[2:17]
	ds_read_b64_tr_b16 v[222:223], v165 offset:0x600
	ds_read_b64_tr_b16 v[224:225], v165 offset:0xe00
	v_mfma_f32_32x32x16_bf16 v[2:17], v[134:137], v[226:229], v[2:17]
	ds_read_b64_tr_b16 v[226:227], v165 offset:0x1600
	ds_read_b64_tr_b16 v[228:229], v165 offset:0x1e00
	v_mfma_f32_32x32x16_bf16 v[2:17], v[138:141], v[230:233], v[2:17]
	ds_read_b64_tr_b16 v[230:231], v165 offset:0x2600
	ds_read_b64_tr_b16 v[232:233], v165 offset:0x2e00
	ds_read_b64_tr_b16 v[238:239], v165 offset:0x3600
	ds_read_b64_tr_b16 v[240:241], v165 offset:0x3e00
	s_waitcnt lgkmcnt(0)
	v_mfma_f32_32x32x16_bf16 v[2:17], v[142:145], v[234:237], v[2:17]
	v_mfma_f32_32x32x16_bf16 v[50:65], v[130:133], v[222:225], v[50:65]
	v_max_f32_e32 v198, v83, v83
	v_max_f32_e32 v234, v82, v82
	v_max_f32_e32 v198, v234, v198
	v_max3_f32 v198, v198, v84, v85
	v_max3_f32 v198, v198, v86, v87
	v_max3_f32 v130, v198, v88, v89
	v_max3_f32 v130, v130, v90, v91
	v_max3_f32 v130, v130, v92, v93
	v_mfma_f32_32x32x16_bf16 v[50:65], v[134:137], v[226:229], v[50:65]
	v_max3_f32 v130, v130, v94, v95
	v_max3_f32 v130, v130, v96, v97
	v_max3_f32 v130, v130, v66, v67
	v_max3_f32 v130, v130, v68, v69
	v_max3_f32 v130, v130, v70, v71
	v_max3_f32 v130, v130, v72, v73
	v_max3_f32 v130, v130, v74, v75
	v_max3_f32 v130, v130, v76, v77
	v_mfma_f32_32x32x16_bf16 v[50:65], v[138:141], v[230:233], v[50:65]
	v_max3_f32 v130, v130, v78, v79
	v_max3_f32 v130, v130, v80, v81
	v_mov_b32_e32 v131, v130
	s_nop 1
	v_permlane32_swap_b32_e32 v130, v131
	v_max_f32_e32 v131, v131, v131
	v_max_f32_e32 v130, v130, v130
	v_max_f32_e32 v130, v130, v131
	v_max_f32_e32 v132, v191, v191
	v_sub_f32_e32 v131, v130, v191
	v_max_f32_e32 v130, v132, v130
	v_mfma_f32_32x32x16_bf16 v[50:65], v[142:145], v[238:241], v[50:65]
	v_sub_f32_e32 v132, v191, v130
	v_mul_f32_e32 v132, 0x3fb8aa3b, v132
	v_exp_f32_e32 v132, v132
	v_cmp_ge_f32_e32 vcc, s54, v131
	s_cmp_eq_u64 vcc, exec
	s_cselect_b64 s[2:3], -1, 0
	s_barrier
	v_cndmask_b32_e64 v198, v132, 1.0, s[2:3]
	v_cmp_gt_f32_e32 vcc, 1.0, v198
	s_waitcnt vmcnt(4)
	ds_write_b128 v166, v[200:203] offset:16384
	s_waitcnt vmcnt(2)
	ds_write_b128 v167, v[210:213] offset:16384
	ds_write_b128 v168, v[204:207] offset:49152
	s_waitcnt vmcnt(1)
	ds_write_b128 v169, v[214:217] offset:49152
	s_waitcnt vmcnt(0)
	ds_write_b128 v186, v[218:221]
	s_cbranch_vccz .LBB0_2236
	s_and_saveexec_b64 s[10:11], s[0:1]
	ds_write_b32 v188, v198 offset:128
	s_or_b64 exec, exec, s[10:11]
	s_waitcnt lgkmcnt(0)
	v_add_u32_e32 v131, s56, v156
	ds_read_b128 v[132:135], v131 offset:224
	ds_read_b128 v[136:139], v131 offset:192
	ds_read_b128 v[140:143], v131 offset:160
	ds_read_b128 v[200:203], v131 offset:128
	s_waitcnt lgkmcnt(3)
	v_pk_mul_f32 v[46:47], v[46:47], v[132:133]
	s_waitcnt lgkmcnt(2)
	v_pk_mul_f32 v[42:43], v[42:43], v[136:137]
	s_waitcnt lgkmcnt(1)
	v_pk_mul_f32 v[38:39], v[38:39], v[140:141]
	v_pk_mul_f32 v[48:49], v[48:49], v[134:135]
	v_pk_mul_f32 v[44:45], v[44:45], v[138:139]
	v_pk_mul_f32 v[40:41], v[40:41], v[142:143]
	s_waitcnt lgkmcnt(0)
	v_pk_mul_f32 v[36:37], v[36:37], v[202:203]
	v_pk_mul_f32 v[34:35], v[34:35], v[200:201]
	v_pk_mul_f32 v[30:31], v[30:31], v[132:133]
	v_pk_mul_f32 v[26:27], v[26:27], v[136:137]
	v_pk_mul_f32 v[22:23], v[22:23], v[140:141]
	v_pk_mul_f32 v[32:33], v[32:33], v[134:135]
	v_pk_mul_f32 v[28:29], v[28:29], v[138:139]
	v_pk_mul_f32 v[24:25], v[24:25], v[142:143]
	v_pk_mul_f32 v[20:21], v[20:21], v[202:203]
	v_pk_mul_f32 v[18:19], v[18:19], v[200:201]
	v_pk_mul_f32 v[14:15], v[14:15], v[132:133]
	v_pk_mul_f32 v[10:11], v[10:11], v[136:137]
	v_pk_mul_f32 v[6:7], v[6:7], v[140:141]
	v_pk_mul_f32 v[16:17], v[16:17], v[134:135]
	v_pk_mul_f32 v[12:13], v[12:13], v[138:139]
	v_pk_mul_f32 v[8:9], v[8:9], v[142:143]
	v_pk_mul_f32 v[4:5], v[4:5], v[202:203]
	v_pk_mul_f32 v[2:3], v[2:3], v[200:201]
	v_pk_mul_f32 v[62:63], v[62:63], v[132:133]
	v_pk_mul_f32 v[58:59], v[58:59], v[136:137]
	v_pk_mul_f32 v[54:55], v[54:55], v[140:141]
	v_pk_mul_f32 v[64:65], v[64:65], v[134:135]
	v_pk_mul_f32 v[60:61], v[60:61], v[138:139]
	v_pk_mul_f32 v[56:57], v[56:57], v[142:143]
	v_pk_mul_f32 v[52:53], v[52:53], v[202:203]
	v_pk_mul_f32 v[50:51], v[50:51], v[200:201]

.LBB0_2897:
	v_max_f32_e32 v131, v83, v83
	v_max_f32_e32 v132, v82, v82
	v_max_f32_e32 v131, v132, v131
	v_max3_f32 v131, v131, v84, v85
	v_max3_f32 v131, v131, v86, v87
	v_max3_f32 v131, v131, v88, v89
	v_max3_f32 v131, v131, v90, v91
	v_max3_f32 v131, v131, v92, v93
	v_max3_f32 v131, v131, v94, v95
	v_max3_f32 v131, v131, v96, v97
	v_max3_f32 v131, v131, v66, v67
	v_max3_f32 v131, v131, v68, v69
	v_max3_f32 v131, v131, v70, v71
	v_max3_f32 v131, v131, v72, v73
	v_max3_f32 v131, v131, v74, v75
	v_max3_f32 v131, v131, v76, v77
	v_max3_f32 v131, v131, v78, v79
	v_max3_f32 v131, v131, v80, v81
	v_mov_b32_e32 v132, v131
	s_nop 1
	v_permlane32_swap_b32_e32 v131, v132
	v_max_f32_e32 v132, v132, v132
	v_max_f32_e32 v131, v131, v131
	v_max_f32_e32 v131, v131, v132
	v_max_f32_e32 v133, v130, v130
	v_sub_f32_e32 v132, v131, v130
	v_max_f32_e32 v131, v133, v131
	v_sub_f32_e32 v133, v130, v131
	v_mul_f32_e32 v133, 0x3fb8aa3b, v133
	v_exp_f32_e32 v133, v133
	v_cmp_ge_f32_e32 vcc, s53, v132
	s_cmp_eq_u64 vcc, exec
	s_cselect_b64 s[0:1], -1, 0
	s_barrier
	v_cndmask_b32_e64 v223, v133, 1.0, s[0:1]
	v_cmp_gt_f32_e32 vcc, 1.0, v223
	s_waitcnt vmcnt(3)
	ds_write_b128 v200, v[114:117]
	s_waitcnt vmcnt(2)
	ds_write_b128 v201, v[118:121]
	s_waitcnt vmcnt(1)
	ds_write_b128 v202, v[122:125] offset:32768
	s_waitcnt vmcnt(0)
	ds_write_b128 v203, v[126:129] offset:32768
	s_cbranch_vccz .LBB0_2901
	s_and_saveexec_b64 s[6:7], s[4:5]
	ds_write_b32 v213, v223 offset:128
	s_or_b64 exec, exec, s[6:7]
	s_waitcnt lgkmcnt(0)
	v_add_u32_e32 v126, s47, v158
	ds_read_b128 v[114:117], v126 offset:224
	ds_read_b128 v[118:121], v126 offset:192
	ds_read_b128 v[122:125], v126 offset:160
	ds_read_b128 v[126:129], v126 offset:128
	s_waitcnt lgkmcnt(3)
	v_pk_mul_f32 v[62:63], v[62:63], v[114:115]
	s_waitcnt lgkmcnt(2)
	v_pk_mul_f32 v[58:59], v[58:59], v[118:119]
	s_waitcnt lgkmcnt(1)
	v_pk_mul_f32 v[54:55], v[54:55], v[122:123]
	v_pk_mul_f32 v[64:65], v[64:65], v[116:117]
	v_pk_mul_f32 v[60:61], v[60:61], v[120:121]
	v_pk_mul_f32 v[56:57], v[56:57], v[124:125]
	s_waitcnt lgkmcnt(0)
	v_pk_mul_f32 v[52:53], v[52:53], v[128:129]
	v_pk_mul_f32 v[50:51], v[50:51], v[126:127]
	v_pk_mul_f32 v[46:47], v[46:47], v[114:115]
	v_pk_mul_f32 v[42:43], v[42:43], v[118:119]
	v_pk_mul_f32 v[38:39], v[38:39], v[122:123]
	v_pk_mul_f32 v[48:49], v[48:49], v[116:117]
	v_pk_mul_f32 v[44:45], v[44:45], v[120:121]
	v_pk_mul_f32 v[40:41], v[40:41], v[124:125]
	v_pk_mul_f32 v[36:37], v[36:37], v[128:129]
	v_pk_mul_f32 v[34:35], v[34:35], v[126:127]
	v_pk_mul_f32 v[30:31], v[30:31], v[114:115]
	v_pk_mul_f32 v[26:27], v[26:27], v[118:119]
	v_pk_mul_f32 v[22:23], v[22:23], v[122:123]
	v_pk_mul_f32 v[32:33], v[32:33], v[116:117]
	v_pk_mul_f32 v[28:29], v[28:29], v[120:121]
	v_pk_mul_f32 v[24:25], v[24:25], v[124:125]
	v_pk_mul_f32 v[20:21], v[20:21], v[128:129]
	v_pk_mul_f32 v[18:19], v[18:19], v[126:127]
	v_pk_mul_f32 v[14:15], v[14:15], v[114:115]
	v_pk_mul_f32 v[10:11], v[10:11], v[118:119]
	v_pk_mul_f32 v[6:7], v[6:7], v[122:123]
	v_pk_mul_f32 v[16:17], v[16:17], v[116:117]
	v_pk_mul_f32 v[12:13], v[12:13], v[120:121]
	v_pk_mul_f32 v[8:9], v[8:9], v[124:125]
	v_pk_mul_f32 v[4:5], v[4:5], v[128:129]
	v_pk_mul_f32 v[2:3], v[2:3], v[126:127]

.LBB0_2939:
	v_max_f32_e32 v130, v83, v83
	v_max_f32_e32 v131, v82, v82
	v_max_f32_e32 v130, v131, v130
	v_max3_f32 v130, v130, v84, v85
	v_max3_f32 v130, v130, v86, v87
	v_max3_f32 v130, v130, v88, v89
	v_max3_f32 v130, v130, v90, v91
	v_max3_f32 v130, v130, v92, v93
	v_max3_f32 v130, v130, v94, v95
	v_max3_f32 v130, v130, v96, v97
	v_max3_f32 v130, v130, v66, v67
	v_max3_f32 v130, v130, v68, v69
	v_max3_f32 v130, v130, v70, v71
	v_max3_f32 v130, v130, v72, v73
	v_max3_f32 v130, v130, v74, v75
	v_max3_f32 v130, v130, v76, v77
	v_max3_f32 v130, v130, v78, v79
	v_max3_f32 v130, v130, v80, v81
	v_mov_b32_e32 v131, v130
	s_nop 1
	v_permlane32_swap_b32_e32 v130, v131
	v_max_f32_e32 v131, v131, v131
	v_max_f32_e32 v130, v130, v130
	v_max_f32_e32 v130, v130, v131
	v_max_f32_e32 v132, v224, v224
	v_sub_f32_e32 v131, v130, v224
	v_max_f32_e32 v130, v132, v130
	v_sub_f32_e32 v132, v224, v130
	v_mul_f32_e32 v132, 0x3fb8aa3b, v132
	v_exp_f32_e32 v132, v132
	v_cmp_ge_f32_e32 vcc, s53, v131
	s_cmp_eq_u64 vcc, exec
	s_cselect_b64 s[0:1], -1, 0
	s_barrier
	v_cndmask_b32_e64 v131, v132, 1.0, s[0:1]
	v_cmp_gt_f32_e32 vcc, 1.0, v131
	s_waitcnt vmcnt(3)
	ds_write_b128 v200, v[114:117] offset:16384
	s_waitcnt vmcnt(2)
	ds_write_b128 v201, v[118:121] offset:16384
	s_waitcnt vmcnt(1)
	ds_write_b128 v202, v[122:125] offset:49152
	s_waitcnt vmcnt(0)
	ds_write_b128 v203, v[126:129] offset:49152
	s_cbranch_vccz .LBB0_2943
	s_and_saveexec_b64 s[6:7], s[4:5]
	ds_write_b32 v213, v131 offset:128
	s_or_b64 exec, exec, s[6:7]
	s_waitcnt lgkmcnt(0)
	v_add_u32_e32 v126, s47, v158
	ds_read_b128 v[114:117], v126 offset:224
	ds_read_b128 v[118:121], v126 offset:192
	ds_read_b128 v[122:125], v126 offset:128
	ds_read_b128 v[126:129], v126 offset:160
	s_waitcnt lgkmcnt(3)
	v_pk_mul_f32 v[64:65], v[64:65], v[116:117]
	v_pk_mul_f32 v[62:63], v[62:63], v[114:115]
	s_waitcnt lgkmcnt(2)
	v_pk_mul_f32 v[60:61], v[60:61], v[120:121]
	v_pk_mul_f32 v[58:59], v[58:59], v[118:119]
	s_waitcnt lgkmcnt(0)
	v_pk_mul_f32 v[56:57], v[56:57], v[128:129]
	v_pk_mul_f32 v[54:55], v[54:55], v[126:127]
	v_pk_mul_f32 v[52:53], v[52:53], v[124:125]
	v_pk_mul_f32 v[50:51], v[50:51], v[122:123]
	v_pk_mul_f32 v[48:49], v[48:49], v[116:117]
	v_pk_mul_f32 v[46:47], v[46:47], v[114:115]
	v_pk_mul_f32 v[44:45], v[44:45], v[120:121]
	v_pk_mul_f32 v[42:43], v[42:43], v[118:119]
	v_pk_mul_f32 v[40:41], v[40:41], v[128:129]
	v_pk_mul_f32 v[38:39], v[38:39], v[126:127]
	v_pk_mul_f32 v[36:37], v[36:37], v[124:125]
	v_pk_mul_f32 v[34:35], v[34:35], v[122:123]
	v_pk_mul_f32 v[32:33], v[32:33], v[116:117]
	v_pk_mul_f32 v[30:31], v[30:31], v[114:115]
	v_pk_mul_f32 v[28:29], v[28:29], v[120:121]
	v_pk_mul_f32 v[26:27], v[26:27], v[118:119]
	v_pk_mul_f32 v[24:25], v[24:25], v[128:129]
	v_pk_mul_f32 v[22:23], v[22:23], v[126:127]
	v_pk_mul_f32 v[20:21], v[20:21], v[124:125]
	v_pk_mul_f32 v[18:19], v[18:19], v[122:123]
	v_pk_mul_f32 v[16:17], v[16:17], v[116:117]
	v_pk_mul_f32 v[14:15], v[14:15], v[114:115]
	v_pk_mul_f32 v[12:13], v[12:13], v[120:121]
	v_pk_mul_f32 v[10:11], v[10:11], v[118:119]
	v_pk_mul_f32 v[8:9], v[8:9], v[128:129]
	v_pk_mul_f32 v[6:7], v[6:7], v[126:127]
	v_pk_mul_f32 v[4:5], v[4:5], v[124:125]
	v_pk_mul_f32 v[2:3], v[2:3], v[122:123]
